# GEMM1 steady trips and GEMM2 trips re-sequenced from 8 phases to 4 (16 -> 8 barriers per trip): each wave group reads fragments for two MMA blocks, then runs 32 MFMAs; LDS-DMA stages regrouped to keep
# speedup vs baseline: 1.0300x; 1.0097x over previous
.Lgb_body2:
	ds_read_b128 v[130:133], v254
	ds_read_b128 v[134:137], v254 offset:1024
	ds_read_b128 v[138:141], v254 offset:2048
	ds_read_b128 v[142:145], v254 offset:3072
	s_mov_b32 m0, s79
	s_add_u32 s98, s44, s0
	s_addc_u32 s99, s45, s1
	ds_read_b128 v[170:173], v165
	ds_read_b128 v[174:177], v165 offset:1024
	ds_read_b128 v[178:181], v165 offset:2048
	ds_read_b128 v[182:185], v165 offset:3072
	ds_read_b128 v[186:189], v165 offset:4096
	ds_read_b128 v[190:193], v165 offset:5120
	ds_read_b128 v[194:197], v165 offset:6144
	ds_read_b128 v[198:201], v165 offset:7168
	global_load_lds_dwordx4 v160, s[44:45]
	s_mov_b32 m0, s80
	s_nop 0
	global_load_lds_dwordx4 v160, s[98:99]
	ds_read_b128 v[202:205], v254 offset:16384
	ds_read_b128 v[206:209], v254 offset:17408
	ds_read_b128 v[210:213], v254 offset:18432
	ds_read_b128 v[214:217], v254 offset:19456
	s_waitcnt lgkmcnt(0)
	s_barrier
	v_mfma_f32_16x16x32_f16 v[58:61], v[130:133], v[170:173], v[58:61]
	v_mfma_f32_16x16x32_f16 v[62:65], v[138:141], v[170:173], v[62:65]
	v_mfma_f32_16x16x32_f16 v[50:53], v[130:133], v[178:181], v[50:53]
	v_mfma_f32_16x16x32_f16 v[54:57], v[138:141], v[178:181], v[54:57]
	v_mfma_f32_16x16x32_f16 v[42:45], v[130:133], v[186:189], v[42:45]
	v_mfma_f32_16x16x32_f16 v[46:49], v[138:141], v[186:189], v[46:49]
	v_mfma_f32_16x16x32_f16 v[26:29], v[130:133], v[194:197], v[26:29]
	v_mfma_f32_16x16x32_f16 v[30:33], v[138:141], v[194:197], v[30:33]
	v_mfma_f32_16x16x32_f16 v[58:61], v[134:137], v[174:177], v[58:61]
	v_mfma_f32_16x16x32_f16 v[62:65], v[142:145], v[174:177], v[62:65]
	v_mfma_f32_16x16x32_f16 v[50:53], v[134:137], v[182:185], v[50:53]
	v_mfma_f32_16x16x32_f16 v[54:57], v[142:145], v[182:185], v[54:57]
	v_mfma_f32_16x16x32_f16 v[42:45], v[134:137], v[190:193], v[42:45]
	v_mfma_f32_16x16x32_f16 v[46:49], v[142:145], v[190:193], v[46:49]
	v_mfma_f32_16x16x32_f16 v[26:29], v[134:137], v[198:201], v[26:29]
	v_mfma_f32_16x16x32_f16 v[30:33], v[142:145], v[198:201], v[30:33]
	v_mfma_f32_16x16x32_f16 v[122:125], v[202:205], v[170:173], v[122:125]
	v_mfma_f32_16x16x32_f16 v[126:129], v[210:213], v[170:173], v[126:129]
	v_mfma_f32_16x16x32_f16 v[114:117], v[202:205], v[178:181], v[114:117]
	v_mfma_f32_16x16x32_f16 v[118:121], v[210:213], v[178:181], v[118:121]
	v_mfma_f32_16x16x32_f16 v[106:109], v[202:205], v[186:189], v[106:109]
	v_mfma_f32_16x16x32_f16 v[110:113], v[210:213], v[186:189], v[110:113]
	v_mfma_f32_16x16x32_f16 v[98:101], v[202:205], v[194:197], v[98:101]
	v_mfma_f32_16x16x32_f16 v[102:105], v[210:213], v[194:197], v[102:105]
	v_mfma_f32_16x16x32_f16 v[122:125], v[206:209], v[174:177], v[122:125]
	v_mfma_f32_16x16x32_f16 v[126:129], v[214:217], v[174:177], v[126:129]
	v_mfma_f32_16x16x32_f16 v[114:117], v[206:209], v[182:185], v[114:117]
	v_mfma_f32_16x16x32_f16 v[118:121], v[214:217], v[182:185], v[118:121]
	v_mfma_f32_16x16x32_f16 v[106:109], v[206:209], v[190:193], v[106:109]
	v_mfma_f32_16x16x32_f16 v[110:113], v[214:217], v[190:193], v[110:113]
	v_mfma_f32_16x16x32_f16 v[98:101], v[206:209], v[198:201], v[98:101]
	v_mfma_f32_16x16x32_f16 v[102:105], v[214:217], v[198:201], v[102:105]
	s_barrier
	s_mov_b32 m0, s51
	s_add_u32 s98, s94, s0
	s_addc_u32 s99, s95, s1
	ds_read_b128 v[170:173], v165 offset:16384
	ds_read_b128 v[174:177], v165 offset:17408
	ds_read_b128 v[178:181], v165 offset:18432
	ds_read_b128 v[182:185], v165 offset:19456
	ds_read_b128 v[186:189], v165 offset:20480
	ds_read_b128 v[190:193], v165 offset:21504
	ds_read_b128 v[194:197], v165 offset:22528
	ds_read_b128 v[198:201], v165 offset:23552
	global_load_lds_dwordx4 v146, s[94:95]
	s_mov_b32 m0, s56
	s_nop 0
	global_load_lds_dwordx4 v146, s[98:99]
	s_mov_b32 m0, s54
	s_add_u32 s96, s46, s30
	global_load_lds_dwordx4 v148, s[46:47]
	s_addc_u32 s97, s47, s31
	s_mov_b32 m0, s55
	global_load_lds_dwordx4 v148, s[96:97]
	s_add_u32 s44, s44, 0x100
	s_addc_u32 s45, s45, 0
	s_add_u32 s91, s91, 0x100
	s_addc_u32 s92, s92, 0
	s_add_u32 s46, s46, s18
	s_addc_u32 s47, s47, s19
	s_mov_b32 m0, s57
	global_load_lds_dwordx4 v148, s[46:47]
	s_add_u32 s46, s46, s30
	s_addc_u32 s47, s47, s31
	s_mov_b32 m0, s60
	global_load_lds_dwordx4 v148, s[46:47]
	s_waitcnt vmcnt(6)
	s_waitcnt lgkmcnt(0)
	s_barrier
	v_mfma_f32_16x16x32_f16 v[34:37], v[130:133], v[170:173], v[34:37]
	v_mfma_f32_16x16x32_f16 v[38:41], v[138:141], v[170:173], v[38:41]
	v_mfma_f32_16x16x32_f16 v[18:21], v[130:133], v[178:181], v[18:21]
	v_mfma_f32_16x16x32_f16 v[22:25], v[138:141], v[178:181], v[22:25]
	v_mfma_f32_16x16x32_f16 v[10:13], v[130:133], v[186:189], v[10:13]
	v_mfma_f32_16x16x32_f16 v[14:17], v[138:141], v[186:189], v[14:17]
	v_mfma_f32_16x16x32_f16 v[2:5], v[130:133], v[194:197], v[2:5]
	v_mfma_f32_16x16x32_f16 v[6:9], v[138:141], v[194:197], v[6:9]
	v_mfma_f32_16x16x32_f16 v[34:37], v[134:137], v[174:177], v[34:37]
	v_mfma_f32_16x16x32_f16 v[38:41], v[142:145], v[174:177], v[38:41]
	v_mfma_f32_16x16x32_f16 v[18:21], v[134:137], v[182:185], v[18:21]
	v_mfma_f32_16x16x32_f16 v[22:25], v[142:145], v[182:185], v[22:25]
	v_mfma_f32_16x16x32_f16 v[10:13], v[134:137], v[190:193], v[10:13]
	v_mfma_f32_16x16x32_f16 v[14:17], v[142:145], v[190:193], v[14:17]
	v_mfma_f32_16x16x32_f16 v[2:5], v[134:137], v[198:201], v[2:5]
	v_mfma_f32_16x16x32_f16 v[6:9], v[142:145], v[198:201], v[6:9]
	v_mfma_f32_16x16x32_f16 v[90:93], v[202:205], v[170:173], v[90:93]
	v_mfma_f32_16x16x32_f16 v[94:97], v[210:213], v[170:173], v[94:97]
	v_mfma_f32_16x16x32_f16 v[82:85], v[202:205], v[178:181], v[82:85]
	v_mfma_f32_16x16x32_f16 v[86:89], v[210:213], v[178:181], v[86:89]
	v_mfma_f32_16x16x32_f16 v[74:77], v[202:205], v[186:189], v[74:77]
	v_mfma_f32_16x16x32_f16 v[78:81], v[210:213], v[186:189], v[78:81]
	v_mfma_f32_16x16x32_f16 v[70:73], v[202:205], v[194:197], v[70:73]
	v_mfma_f32_16x16x32_f16 v[66:69], v[210:213], v[194:197], v[66:69]
	v_mfma_f32_16x16x32_f16 v[90:93], v[206:209], v[174:177], v[90:93]
	v_mfma_f32_16x16x32_f16 v[94:97], v[214:217], v[174:177], v[94:97]
	v_mfma_f32_16x16x32_f16 v[82:85], v[206:209], v[182:185], v[82:85]
	v_mfma_f32_16x16x32_f16 v[86:89], v[214:217], v[182:185], v[86:89]
	v_mfma_f32_16x16x32_f16 v[74:77], v[206:209], v[190:193], v[74:77]
	v_mfma_f32_16x16x32_f16 v[78:81], v[214:217], v[190:193], v[78:81]
	v_mfma_f32_16x16x32_f16 v[70:73], v[206:209], v[198:201], v[70:73]
	v_mfma_f32_16x16x32_f16 v[66:69], v[214:217], v[198:201], v[66:69]
	s_barrier
	ds_read_b128 v[130:133], v254 offset:32768
	ds_read_b128 v[134:137], v254 offset:33792
	ds_read_b128 v[138:141], v254 offset:34816
	ds_read_b128 v[142:145], v254 offset:35840
	s_mov_b32 m0, s61
	s_add_u32 s98, s94, s8
	s_addc_u32 s99, s95, s9
	ds_read_b128 v[170:173], v165 offset:32768
	ds_read_b128 v[174:177], v165 offset:33792
	ds_read_b128 v[178:181], v165 offset:34816
	ds_read_b128 v[182:185], v165 offset:35840
	ds_read_b128 v[186:189], v165 offset:36864
	ds_read_b128 v[190:193], v165 offset:37888
	ds_read_b128 v[194:197], v165 offset:38912
	ds_read_b128 v[198:201], v165 offset:39936
	global_load_lds_dwordx4 v146, s[98:99]
	s_add_u32 s98, s94, s12
	s_addc_u32 s99, s95, s13
	s_mov_b32 m0, s62
	s_nop 0
	global_load_lds_dwordx4 v146, s[98:99]
	ds_read_b128 v[202:205], v254 offset:49152
	ds_read_b128 v[206:209], v254 offset:50176
	ds_read_b128 v[210:213], v254 offset:51200
	ds_read_b128 v[214:217], v254 offset:52224
	s_waitcnt lgkmcnt(0)
	s_barrier
	v_mfma_f32_16x16x32_f16 v[58:61], v[130:133], v[170:173], v[58:61]
	v_mfma_f32_16x16x32_f16 v[62:65], v[138:141], v[170:173], v[62:65]
	v_mfma_f32_16x16x32_f16 v[50:53], v[130:133], v[178:181], v[50:53]
	v_mfma_f32_16x16x32_f16 v[54:57], v[138:141], v[178:181], v[54:57]
	v_mfma_f32_16x16x32_f16 v[42:45], v[130:133], v[186:189], v[42:45]
	v_mfma_f32_16x16x32_f16 v[46:49], v[138:141], v[186:189], v[46:49]
	v_mfma_f32_16x16x32_f16 v[26:29], v[130:133], v[194:197], v[26:29]
	v_mfma_f32_16x16x32_f16 v[30:33], v[138:141], v[194:197], v[30:33]
	v_mfma_f32_16x16x32_f16 v[58:61], v[134:137], v[174:177], v[58:61]
	v_mfma_f32_16x16x32_f16 v[62:65], v[142:145], v[174:177], v[62:65]
	v_mfma_f32_16x16x32_f16 v[50:53], v[134:137], v[182:185], v[50:53]
	v_mfma_f32_16x16x32_f16 v[54:57], v[142:145], v[182:185], v[54:57]
	v_mfma_f32_16x16x32_f16 v[42:45], v[134:137], v[190:193], v[42:45]
	v_mfma_f32_16x16x32_f16 v[46:49], v[142:145], v[190:193], v[46:49]
	v_mfma_f32_16x16x32_f16 v[26:29], v[134:137], v[198:201], v[26:29]
	v_mfma_f32_16x16x32_f16 v[30:33], v[142:145], v[198:201], v[30:33]
	v_mfma_f32_16x16x32_f16 v[122:125], v[202:205], v[170:173], v[122:125]
	v_mfma_f32_16x16x32_f16 v[126:129], v[210:213], v[170:173], v[126:129]
	v_mfma_f32_16x16x32_f16 v[114:117], v[202:205], v[178:181], v[114:117]
	v_mfma_f32_16x16x32_f16 v[118:121], v[210:213], v[178:181], v[118:121]
	v_mfma_f32_16x16x32_f16 v[106:109], v[202:205], v[186:189], v[106:109]
	v_mfma_f32_16x16x32_f16 v[110:113], v[210:213], v[186:189], v[110:113]
	v_mfma_f32_16x16x32_f16 v[98:101], v[202:205], v[194:197], v[98:101]
	v_mfma_f32_16x16x32_f16 v[102:105], v[210:213], v[194:197], v[102:105]
	v_mfma_f32_16x16x32_f16 v[122:125], v[206:209], v[174:177], v[122:125]
	v_mfma_f32_16x16x32_f16 v[126:129], v[214:217], v[174:177], v[126:129]
	v_mfma_f32_16x16x32_f16 v[114:117], v[206:209], v[182:185], v[114:117]
	v_mfma_f32_16x16x32_f16 v[118:121], v[214:217], v[182:185], v[118:121]
	v_mfma_f32_16x16x32_f16 v[106:109], v[206:209], v[190:193], v[106:109]
	v_mfma_f32_16x16x32_f16 v[110:113], v[214:217], v[190:193], v[110:113]
	v_mfma_f32_16x16x32_f16 v[98:101], v[206:209], v[198:201], v[98:101]
	v_mfma_f32_16x16x32_f16 v[102:105], v[214:217], v[198:201], v[102:105]
	s_barrier
	s_mov_b32 m0, s65
	s_add_u32 s98, s94, s14
	s_addc_u32 s99, s95, s15
	ds_read_b128 v[170:173], v165 offset:49152
	ds_read_b128 v[174:177], v165 offset:50176
	ds_read_b128 v[178:181], v165 offset:51200
	ds_read_b128 v[182:185], v165 offset:52224
	ds_read_b128 v[186:189], v165 offset:53248
	ds_read_b128 v[190:193], v165 offset:54272
	ds_read_b128 v[194:197], v165 offset:55296
	ds_read_b128 v[198:201], v165 offset:56320
	global_load_lds_dwordx4 v146, s[98:99]
	s_add_u32 s98, s94, s16
	s_addc_u32 s99, s95, s17
	s_mov_b32 m0, s72
	s_nop 0
	global_load_lds_dwordx4 v146, s[98:99]
	s_mov_b32 m0, s63
	s_add_u32 s96, s96, s14
	s_addc_u32 s97, s97, s15
	s_sub_u32 s98, s96, s30
	s_subb_u32 s99, s97, s31
	global_load_lds_dwordx4 v148, s[98:99]
	s_mov_b32 m0, s64
	s_nop 0
	global_load_lds_dwordx4 v148, s[96:97]
	s_mov_b32 m0, s73
	s_add_u32 s46, s46, s14
	s_addc_u32 s47, s47, s15
	s_sub_u32 s98, s46, s30
	s_subb_u32 s99, s47, s31
	global_load_lds_dwordx4 v148, s[98:99]
	s_mov_b32 m0, s74
	s_nop 0
	global_load_lds_dwordx4 v148, s[46:47]
	s_waitcnt vmcnt(6)
	s_waitcnt lgkmcnt(0)
	s_barrier
	v_mfma_f32_16x16x32_f16 v[34:37], v[130:133], v[170:173], v[34:37]
	v_mfma_f32_16x16x32_f16 v[38:41], v[138:141], v[170:173], v[38:41]
	v_mfma_f32_16x16x32_f16 v[18:21], v[130:133], v[178:181], v[18:21]
	v_mfma_f32_16x16x32_f16 v[22:25], v[138:141], v[178:181], v[22:25]
	v_mfma_f32_16x16x32_f16 v[10:13], v[130:133], v[186:189], v[10:13]
	v_mfma_f32_16x16x32_f16 v[14:17], v[138:141], v[186:189], v[14:17]
	v_mfma_f32_16x16x32_f16 v[2:5], v[130:133], v[194:197], v[2:5]
	v_mfma_f32_16x16x32_f16 v[6:9], v[138:141], v[194:197], v[6:9]
	v_mfma_f32_16x16x32_f16 v[34:37], v[134:137], v[174:177], v[34:37]
	v_mfma_f32_16x16x32_f16 v[38:41], v[142:145], v[174:177], v[38:41]
	v_mfma_f32_16x16x32_f16 v[18:21], v[134:137], v[182:185], v[18:21]
	v_mfma_f32_16x16x32_f16 v[22:25], v[142:145], v[182:185], v[22:25]
	v_mfma_f32_16x16x32_f16 v[10:13], v[134:137], v[190:193], v[10:13]
	v_mfma_f32_16x16x32_f16 v[14:17], v[142:145], v[190:193], v[14:17]
	v_mfma_f32_16x16x32_f16 v[2:5], v[134:137], v[198:201], v[2:5]
	v_mfma_f32_16x16x32_f16 v[6:9], v[142:145], v[198:201], v[6:9]
	v_mfma_f32_16x16x32_f16 v[90:93], v[202:205], v[170:173], v[90:93]
	v_mfma_f32_16x16x32_f16 v[94:97], v[210:213], v[170:173], v[94:97]
	v_mfma_f32_16x16x32_f16 v[82:85], v[202:205], v[178:181], v[82:85]
	v_mfma_f32_16x16x32_f16 v[86:89], v[210:213], v[178:181], v[86:89]
	v_mfma_f32_16x16x32_f16 v[74:77], v[202:205], v[186:189], v[74:77]
	v_mfma_f32_16x16x32_f16 v[78:81], v[210:213], v[186:189], v[78:81]
	v_mfma_f32_16x16x32_f16 v[70:73], v[202:205], v[194:197], v[70:73]
	v_mfma_f32_16x16x32_f16 v[66:69], v[210:213], v[194:197], v[66:69]
	v_mfma_f32_16x16x32_f16 v[90:93], v[206:209], v[174:177], v[90:93]
	v_mfma_f32_16x16x32_f16 v[94:97], v[214:217], v[174:177], v[94:97]
	v_mfma_f32_16x16x32_f16 v[82:85], v[206:209], v[182:185], v[82:85]
	v_mfma_f32_16x16x32_f16 v[86:89], v[214:217], v[182:185], v[86:89]
	v_mfma_f32_16x16x32_f16 v[74:77], v[206:209], v[190:193], v[74:77]
	v_mfma_f32_16x16x32_f16 v[78:81], v[214:217], v[190:193], v[78:81]
	v_mfma_f32_16x16x32_f16 v[70:73], v[206:209], v[198:201], v[70:73]
	v_mfma_f32_16x16x32_f16 v[66:69], v[214:217], v[198:201], v[66:69]
	s_add_i32 s93, s93, 2
	s_cmp_gt_u32 s93, 13
	s_barrier
	s_cbranch_scc1 .LBB0_264
	s_cmp_eq_u32 s93, 12
	s_cbranch_scc1 .Lgb_last
	s_add_u32 s94, s44, 0xfffc0080
	s_addc_u32 s95, s45, -1
	s_mov_b32 s47, s92
	s_mov_b32 s46, s91
	s_branch .Lgb_body2

.Lg2_body2:
	ds_read_b128 v[136:139], v254
	ds_read_b128 v[144:147], v254 offset:1024
	ds_read_b128 v[148:151], v254 offset:2048
	ds_read_b128 v[152:155], v254 offset:3072
	s_mov_b32 m0, s79
	ds_read_b128 v[156:159], v141
	ds_read_b128 v[160:163], v141 offset:1024
	ds_read_b128 v[164:167], v141 offset:2048
	ds_read_b128 v[168:171], v141 offset:3072
	ds_read_b128 v[172:175], v141 offset:4096
	ds_read_b128 v[176:179], v141 offset:5120
	ds_read_b128 v[180:183], v141 offset:6144
	ds_read_b128 v[184:187], v141 offset:7168
	global_load_lds_dwordx4 v134, s[44:45]
	s_mov_b32 m0, s80
	s_add_u32 s98, s44, s16
	s_addc_u32 s99, s45, s17
	global_load_lds_dwordx4 v134, s[98:99]
	ds_read_b128 v[188:191], v254 offset:16384
	ds_read_b128 v[192:195], v254 offset:17408
	ds_read_b128 v[196:199], v254 offset:18432
	ds_read_b128 v[200:203], v254 offset:19456
	s_waitcnt lgkmcnt(0)
	s_barrier
	v_mfma_f32_16x16x32_f16 v[118:121], v[136:139], v[156:159], v[118:121]
	v_mfma_f32_16x16x32_f16 v[114:117], v[148:151], v[156:159], v[114:117]
	v_mfma_f32_16x16x32_f16 v[102:105], v[136:139], v[164:167], v[102:105]
	v_mfma_f32_16x16x32_f16 v[98:101], v[148:151], v[164:167], v[98:101]
	v_mfma_f32_16x16x32_f16 v[86:89], v[136:139], v[172:175], v[86:89]
	v_mfma_f32_16x16x32_f16 v[82:85], v[148:151], v[172:175], v[82:85]
	v_mfma_f32_16x16x32_f16 v[66:69], v[136:139], v[180:183], v[66:69]
	v_mfma_f32_16x16x32_f16 v[54:57], v[148:151], v[180:183], v[54:57]
	v_mfma_f32_16x16x32_f16 v[118:121], v[144:147], v[160:163], v[118:121]
	v_mfma_f32_16x16x32_f16 v[114:117], v[152:155], v[160:163], v[114:117]
	v_mfma_f32_16x16x32_f16 v[102:105], v[144:147], v[168:171], v[102:105]
	v_mfma_f32_16x16x32_f16 v[98:101], v[152:155], v[168:171], v[98:101]
	v_mfma_f32_16x16x32_f16 v[86:89], v[144:147], v[176:179], v[86:89]
	v_mfma_f32_16x16x32_f16 v[82:85], v[152:155], v[176:179], v[82:85]
	v_mfma_f32_16x16x32_f16 v[66:69], v[144:147], v[184:187], v[66:69]
	v_mfma_f32_16x16x32_f16 v[54:57], v[152:155], v[184:187], v[54:57]
	v_mfma_f32_16x16x32_f16 v[122:125], v[188:191], v[156:159], v[122:125]
	v_mfma_f32_16x16x32_f16 v[126:129], v[196:199], v[156:159], v[126:129]
	v_mfma_f32_16x16x32_f16 v[106:109], v[188:191], v[164:167], v[106:109]
	v_mfma_f32_16x16x32_f16 v[110:113], v[196:199], v[164:167], v[110:113]
	v_mfma_f32_16x16x32_f16 v[90:93], v[188:191], v[172:175], v[90:93]
	v_mfma_f32_16x16x32_f16 v[94:97], v[196:199], v[172:175], v[94:97]
	v_mfma_f32_16x16x32_f16 v[74:77], v[188:191], v[180:183], v[74:77]
	v_mfma_f32_16x16x32_f16 v[78:81], v[196:199], v[180:183], v[78:81]
	v_mfma_f32_16x16x32_f16 v[122:125], v[192:195], v[160:163], v[122:125]
	v_mfma_f32_16x16x32_f16 v[126:129], v[200:203], v[160:163], v[126:129]
	v_mfma_f32_16x16x32_f16 v[106:109], v[192:195], v[168:171], v[106:109]
	v_mfma_f32_16x16x32_f16 v[110:113], v[200:203], v[168:171], v[110:113]
	v_mfma_f32_16x16x32_f16 v[90:93], v[192:195], v[176:179], v[90:93]
	v_mfma_f32_16x16x32_f16 v[94:97], v[200:203], v[176:179], v[94:97]
	v_mfma_f32_16x16x32_f16 v[74:77], v[192:195], v[184:187], v[74:77]
	v_mfma_f32_16x16x32_f16 v[78:81], v[200:203], v[184:187], v[78:81]
	s_barrier
	s_mov_b32 m0, s56
	ds_read_b128 v[156:159], v141 offset:16384
	ds_read_b128 v[160:163], v141 offset:17408
	ds_read_b128 v[164:167], v141 offset:18432
	ds_read_b128 v[168:171], v141 offset:19456
	ds_read_b128 v[172:175], v141 offset:20480
	ds_read_b128 v[176:179], v141 offset:21504
	ds_read_b128 v[180:183], v141 offset:22528
	ds_read_b128 v[184:187], v141 offset:23552
	global_load_lds_dwordx4 v130, s[46:47]
	s_mov_b32 m0, s59
	s_add_u32 s98, s46, s16
	s_addc_u32 s99, s47, s17
	global_load_lds_dwordx4 v130, s[98:99]
	s_mov_b32 m0, s57
	global_load_lds_dwordx4 v132, s[86:87]
	s_mov_b32 m0, s58
	s_add_u32 s98, s86, s14
	s_addc_u32 s99, s87, s15
	global_load_lds_dwordx4 v132, s[98:99]
	s_add_u32 s44, s44, 0x100
	s_addc_u32 s45, s45, 0
	s_add_u32 s51, s51, 0x100
	s_addc_u32 s84, s84, 0
	s_mov_b32 m0, s60
	s_add_u32 s98, s86, s18
	s_addc_u32 s99, s87, s19
	global_load_lds_dwordx4 v132, s[98:99]
	s_mov_b32 m0, s61
	s_add_u32 s98, s86, s16
	s_addc_u32 s99, s87, s17
	global_load_lds_dwordx4 v132, s[98:99]
	s_waitcnt vmcnt(6)
	s_waitcnt lgkmcnt(0)
	s_barrier
	v_mfma_f32_16x16x32_f16 v[58:61], v[136:139], v[156:159], v[58:61]
	v_mfma_f32_16x16x32_f16 v[50:53], v[148:151], v[156:159], v[50:53]
	v_mfma_f32_16x16x32_f16 v[38:41], v[136:139], v[164:167], v[38:41]
	v_mfma_f32_16x16x32_f16 v[34:37], v[148:151], v[164:167], v[34:37]
	v_mfma_f32_16x16x32_f16 v[22:25], v[136:139], v[172:175], v[22:25]
	v_mfma_f32_16x16x32_f16 v[18:21], v[148:151], v[172:175], v[18:21]
	v_mfma_f32_16x16x32_f16 v[10:13], v[136:139], v[180:183], v[10:13]
	v_mfma_f32_16x16x32_f16 v[6:9], v[148:151], v[180:183], v[6:9]
	v_mfma_f32_16x16x32_f16 v[58:61], v[144:147], v[160:163], v[58:61]
	v_mfma_f32_16x16x32_f16 v[50:53], v[152:155], v[160:163], v[50:53]
	v_mfma_f32_16x16x32_f16 v[38:41], v[144:147], v[168:171], v[38:41]
	v_mfma_f32_16x16x32_f16 v[34:37], v[152:155], v[168:171], v[34:37]
	v_mfma_f32_16x16x32_f16 v[22:25], v[144:147], v[176:179], v[22:25]
	v_mfma_f32_16x16x32_f16 v[18:21], v[152:155], v[176:179], v[18:21]
	v_mfma_f32_16x16x32_f16 v[10:13], v[144:147], v[184:187], v[10:13]
	v_mfma_f32_16x16x32_f16 v[6:9], v[152:155], v[184:187], v[6:9]
	v_mfma_f32_16x16x32_f16 v[62:65], v[188:191], v[156:159], v[62:65]
	v_mfma_f32_16x16x32_f16 v[70:73], v[196:199], v[156:159], v[70:73]
	v_mfma_f32_16x16x32_f16 v[42:45], v[188:191], v[164:167], v[42:45]
	v_mfma_f32_16x16x32_f16 v[46:49], v[196:199], v[164:167], v[46:49]
	v_mfma_f32_16x16x32_f16 v[26:29], v[188:191], v[172:175], v[26:29]
	v_mfma_f32_16x16x32_f16 v[30:33], v[196:199], v[172:175], v[30:33]
	v_mfma_f32_16x16x32_f16 v[14:17], v[188:191], v[180:183], v[14:17]
	v_mfma_f32_16x16x32_f16 v[2:5], v[196:199], v[180:183], v[2:5]
	v_mfma_f32_16x16x32_f16 v[62:65], v[192:195], v[160:163], v[62:65]
	v_mfma_f32_16x16x32_f16 v[70:73], v[200:203], v[160:163], v[70:73]
	v_mfma_f32_16x16x32_f16 v[42:45], v[192:195], v[168:171], v[42:45]
	v_mfma_f32_16x16x32_f16 v[46:49], v[200:203], v[168:171], v[46:49]
	v_mfma_f32_16x16x32_f16 v[26:29], v[192:195], v[176:179], v[26:29]
	v_mfma_f32_16x16x32_f16 v[30:33], v[200:203], v[176:179], v[30:33]
	v_mfma_f32_16x16x32_f16 v[14:17], v[192:195], v[184:187], v[14:17]
	v_mfma_f32_16x16x32_f16 v[2:5], v[200:203], v[184:187], v[2:5]
	s_barrier
	ds_read_b128 v[136:139], v254 offset:32768
	ds_read_b128 v[144:147], v254 offset:33792
	ds_read_b128 v[148:151], v254 offset:34816
	ds_read_b128 v[152:155], v254 offset:35840
	s_mov_b32 m0, s62
	ds_read_b128 v[156:159], v141 offset:32768
	ds_read_b128 v[160:163], v141 offset:33792
	ds_read_b128 v[164:167], v141 offset:34816
	ds_read_b128 v[168:171], v141 offset:35840
	ds_read_b128 v[172:175], v141 offset:36864
	ds_read_b128 v[176:179], v141 offset:37888
	ds_read_b128 v[180:183], v141 offset:38912
	ds_read_b128 v[184:187], v141 offset:39936
	s_add_u32 s98, s46, s20
	s_addc_u32 s99, s47, s21
	global_load_lds_dwordx4 v130, s[98:99]
	s_mov_b32 m0, s63
	s_add_u32 s98, s46, s22
	s_addc_u32 s99, s47, s23
	global_load_lds_dwordx4 v130, s[98:99]
	ds_read_b128 v[188:191], v254 offset:49152
	ds_read_b128 v[192:195], v254 offset:50176
	ds_read_b128 v[196:199], v254 offset:51200
	ds_read_b128 v[200:203], v254 offset:52224
	s_waitcnt lgkmcnt(0)
	s_barrier
	v_mfma_f32_16x16x32_f16 v[118:121], v[136:139], v[156:159], v[118:121]
	v_mfma_f32_16x16x32_f16 v[114:117], v[148:151], v[156:159], v[114:117]
	v_mfma_f32_16x16x32_f16 v[102:105], v[136:139], v[164:167], v[102:105]
	v_mfma_f32_16x16x32_f16 v[98:101], v[148:151], v[164:167], v[98:101]
	v_mfma_f32_16x16x32_f16 v[86:89], v[136:139], v[172:175], v[86:89]
	v_mfma_f32_16x16x32_f16 v[82:85], v[148:151], v[172:175], v[82:85]
	v_mfma_f32_16x16x32_f16 v[66:69], v[136:139], v[180:183], v[66:69]
	v_mfma_f32_16x16x32_f16 v[54:57], v[148:151], v[180:183], v[54:57]
	v_mfma_f32_16x16x32_f16 v[118:121], v[144:147], v[160:163], v[118:121]
	v_mfma_f32_16x16x32_f16 v[114:117], v[152:155], v[160:163], v[114:117]
	v_mfma_f32_16x16x32_f16 v[102:105], v[144:147], v[168:171], v[102:105]
	v_mfma_f32_16x16x32_f16 v[98:101], v[152:155], v[168:171], v[98:101]
	v_mfma_f32_16x16x32_f16 v[86:89], v[144:147], v[176:179], v[86:89]
	v_mfma_f32_16x16x32_f16 v[82:85], v[152:155], v[176:179], v[82:85]
	v_mfma_f32_16x16x32_f16 v[66:69], v[144:147], v[184:187], v[66:69]
	v_mfma_f32_16x16x32_f16 v[54:57], v[152:155], v[184:187], v[54:57]
	v_mfma_f32_16x16x32_f16 v[122:125], v[188:191], v[156:159], v[122:125]
	v_mfma_f32_16x16x32_f16 v[126:129], v[196:199], v[156:159], v[126:129]
	v_mfma_f32_16x16x32_f16 v[106:109], v[188:191], v[164:167], v[106:109]
	v_mfma_f32_16x16x32_f16 v[110:113], v[196:199], v[164:167], v[110:113]
	v_mfma_f32_16x16x32_f16 v[90:93], v[188:191], v[172:175], v[90:93]
	v_mfma_f32_16x16x32_f16 v[94:97], v[196:199], v[172:175], v[94:97]
	v_mfma_f32_16x16x32_f16 v[74:77], v[188:191], v[180:183], v[74:77]
	v_mfma_f32_16x16x32_f16 v[78:81], v[196:199], v[180:183], v[78:81]
	v_mfma_f32_16x16x32_f16 v[122:125], v[192:195], v[160:163], v[122:125]
	v_mfma_f32_16x16x32_f16 v[126:129], v[200:203], v[160:163], v[126:129]
	v_mfma_f32_16x16x32_f16 v[106:109], v[192:195], v[168:171], v[106:109]
	v_mfma_f32_16x16x32_f16 v[110:113], v[200:203], v[168:171], v[110:113]
	v_mfma_f32_16x16x32_f16 v[90:93], v[192:195], v[176:179], v[90:93]
	v_mfma_f32_16x16x32_f16 v[94:97], v[200:203], v[176:179], v[94:97]
	v_mfma_f32_16x16x32_f16 v[74:77], v[192:195], v[184:187], v[74:77]
	v_mfma_f32_16x16x32_f16 v[78:81], v[200:203], v[184:187], v[78:81]
	s_barrier
	s_mov_b32 m0, s72
	ds_read_b128 v[156:159], v141 offset:49152
	ds_read_b128 v[160:163], v141 offset:50176
	ds_read_b128 v[164:167], v141 offset:51200
	ds_read_b128 v[168:171], v141 offset:52224
	ds_read_b128 v[172:175], v141 offset:53248
	ds_read_b128 v[176:179], v141 offset:54272
	ds_read_b128 v[180:183], v141 offset:55296
	ds_read_b128 v[184:187], v141 offset:56320
	s_add_u32 s98, s46, s24
	s_addc_u32 s99, s47, s25
	global_load_lds_dwordx4 v130, s[98:99]
	s_mov_b32 m0, s73
	s_add_u32 s98, s46, s28
	s_addc_u32 s99, s47, s29
	global_load_lds_dwordx4 v130, s[98:99]
	s_mov_b32 m0, s64
	s_add_u32 s98, s86, s24
	s_addc_u32 s99, s87, s25
	global_load_lds_dwordx4 v132, s[98:99]
	s_mov_b32 m0, s65
	s_add_u32 s98, s86, s26
	s_addc_u32 s99, s87, s27
	global_load_lds_dwordx4 v132, s[98:99]
	s_mov_b32 m0, s74
	s_add_u32 s98, s86, s30
	s_addc_u32 s99, s87, s31
	global_load_lds_dwordx4 v132, s[98:99]
	s_mov_b32 m0, s75
	s_add_u32 s98, s86, s28
	s_addc_u32 s99, s87, s29
	global_load_lds_dwordx4 v132, s[98:99]
	s_waitcnt vmcnt(6)
	s_waitcnt lgkmcnt(0)
	s_barrier
	v_mfma_f32_16x16x32_f16 v[58:61], v[136:139], v[156:159], v[58:61]
	v_mfma_f32_16x16x32_f16 v[50:53], v[148:151], v[156:159], v[50:53]
	v_mfma_f32_16x16x32_f16 v[38:41], v[136:139], v[164:167], v[38:41]
	v_mfma_f32_16x16x32_f16 v[34:37], v[148:151], v[164:167], v[34:37]
	v_mfma_f32_16x16x32_f16 v[22:25], v[136:139], v[172:175], v[22:25]
	v_mfma_f32_16x16x32_f16 v[18:21], v[148:151], v[172:175], v[18:21]
	v_mfma_f32_16x16x32_f16 v[10:13], v[136:139], v[180:183], v[10:13]
	v_mfma_f32_16x16x32_f16 v[6:9], v[148:151], v[180:183], v[6:9]
	v_mfma_f32_16x16x32_f16 v[58:61], v[144:147], v[160:163], v[58:61]
	v_mfma_f32_16x16x32_f16 v[50:53], v[152:155], v[160:163], v[50:53]
	v_mfma_f32_16x16x32_f16 v[38:41], v[144:147], v[168:171], v[38:41]
	v_mfma_f32_16x16x32_f16 v[34:37], v[152:155], v[168:171], v[34:37]
	v_mfma_f32_16x16x32_f16 v[22:25], v[144:147], v[176:179], v[22:25]
	v_mfma_f32_16x16x32_f16 v[18:21], v[152:155], v[176:179], v[18:21]
	v_mfma_f32_16x16x32_f16 v[10:13], v[144:147], v[184:187], v[10:13]
	v_mfma_f32_16x16x32_f16 v[6:9], v[152:155], v[184:187], v[6:9]
	v_mfma_f32_16x16x32_f16 v[62:65], v[188:191], v[156:159], v[62:65]
	v_mfma_f32_16x16x32_f16 v[70:73], v[196:199], v[156:159], v[70:73]
	v_mfma_f32_16x16x32_f16 v[42:45], v[188:191], v[164:167], v[42:45]
	v_mfma_f32_16x16x32_f16 v[46:49], v[196:199], v[164:167], v[46:49]
	v_mfma_f32_16x16x32_f16 v[26:29], v[188:191], v[172:175], v[26:29]
	v_mfma_f32_16x16x32_f16 v[30:33], v[196:199], v[172:175], v[30:33]
	v_mfma_f32_16x16x32_f16 v[14:17], v[188:191], v[180:183], v[14:17]
	v_mfma_f32_16x16x32_f16 v[2:5], v[196:199], v[180:183], v[2:5]
	v_mfma_f32_16x16x32_f16 v[62:65], v[192:195], v[160:163], v[62:65]
	v_mfma_f32_16x16x32_f16 v[70:73], v[200:203], v[160:163], v[70:73]
	v_mfma_f32_16x16x32_f16 v[42:45], v[192:195], v[168:171], v[42:45]
	v_mfma_f32_16x16x32_f16 v[46:49], v[200:203], v[168:171], v[46:49]
	v_mfma_f32_16x16x32_f16 v[26:29], v[192:195], v[176:179], v[26:29]
	v_mfma_f32_16x16x32_f16 v[30:33], v[200:203], v[176:179], v[30:33]
	v_mfma_f32_16x16x32_f16 v[14:17], v[192:195], v[184:187], v[14:17]
	v_mfma_f32_16x16x32_f16 v[2:5], v[200:203], v[184:187], v[2:5]
	s_add_i32 s85, s85, 2
	s_cmp_gt_u32 s85, 29
	s_barrier
	s_cbranch_scc1 .LBB0_846
	s_cmp_eq_u32 s85, 28
	s_cbranch_scc1 .LBB0_844
	s_add_u32 s46, s44, 0xffe80080
	s_addc_u32 s47, s45, -1
	s_mov_b32 s87, s84
	s_mov_b32 s86, s51
	s_branch .Lg2_body2
